# nsa_partial_blocks_via_bias_fast_path
# speedup vs baseline: 1.0172x; 1.0003x over previous
.Lnsa_fastm:
	v_bfe_i32 v147, v127, 0, 1
	v_bfe_i32 v148, v127, 1, 1
	v_bfe_i32 v149, v127, 2, 1
	v_bfe_i32 v150, v127, 3, 1
	v_bfi_b32 v152, v147, 0, v102
	v_bfi_b32 v153, v148, 0, v102
	v_bfi_b32 v154, v149, 0, v102
	v_bfi_b32 v155, v150, 0, v102
	v_bfe_i32 v147, v127, 4, 1
	v_bfe_i32 v148, v127, 5, 1
	v_bfe_i32 v149, v127, 6, 1
	v_bfe_i32 v150, v127, 7, 1
	v_bfi_b32 v156, v147, 0, v102
	v_bfi_b32 v157, v148, 0, v102
	v_bfi_b32 v158, v149, 0, v102
	v_bfi_b32 v159, v150, 0, v102
	v_bfe_i32 v147, v127, 8, 1
	v_bfe_i32 v148, v127, 9, 1
	v_bfe_i32 v149, v127, 10, 1
	v_bfe_i32 v150, v127, 11, 1
	v_bfi_b32 v160, v147, 0, v102
	v_bfi_b32 v161, v148, 0, v102
	v_bfi_b32 v162, v149, 0, v102
	v_bfi_b32 v163, v150, 0, v102
	v_bfe_i32 v147, v127, 12, 1
	v_bfe_i32 v148, v127, 13, 1
	v_bfe_i32 v149, v127, 14, 1
	v_bfe_i32 v150, v127, 15, 1
	v_bfi_b32 v164, v147, 0, v102
	v_bfi_b32 v165, v148, 0, v102
	v_bfi_b32 v166, v149, 0, v102
	v_bfi_b32 v167, v150, 0, v102
	s_cmp_lg_u32 s63, 0
	s_cbranch_scc1 .Lnsa_fastm1
	ds_read_b128 v[176:179], v175
	ds_read_b128 v[180:183], v211
	ds_read_b128 v[184:187], v228
	ds_read_b128 v[188:191], v229
	ds_read_b128 v[192:195], v175 offset:64
	ds_read_b128 v[196:199], v211 offset:64
	ds_read_b128 v[200:203], v228 offset:64
	ds_read_b128 v[204:207], v229 offset:64
	ds_read_b128 v[212:215], v231 offset:38912
	ds_read_b128 v[216:219], v231 offset:41216
	ds_read_b128 v[220:223], v231 offset:43520
	ds_read_b128 v[224:227], v252 offset:38912
	ds_read_b128 v[232:235], v231 offset:38976
	ds_read_b128 v[236:239], v231 offset:41280
	s_waitcnt lgkmcnt(10)
	v_mfma_f32_16x16x32_bf16 v[52:55], v[176:179], v[4:7], v[152:155]
	v_mfma_f32_16x16x32_bf16 v[48:51], v[180:183], v[4:7], v[156:159]
	ds_read_b128 v[240:243], v231 offset:43584
	v_mfma_f32_16x16x32_bf16 v[44:47], v[184:187], v[4:7], v[160:163]
	ds_read_b128 v[244:247], v252 offset:38976
	v_mfma_f32_16x16x32_bf16 v[40:43], v[188:191], v[4:7], v[164:167]
	s_waitcnt lgkmcnt(8)
	v_mfma_f32_16x16x32_bf16 v[52:55], v[192:195], v[0:3], v[52:55]
	v_mfma_f32_16x16x32_bf16 v[48:51], v[196:199], v[0:3], v[48:51]
	v_mfma_f32_16x16x32_bf16 v[44:47], v[200:203], v[0:3], v[44:47]
	v_mfma_f32_16x16x32_bf16 v[40:43], v[204:207], v[0:3], v[40:43]
	s_nop 4
	v_max3_f32 v90, v52, v53, v54
	v_max3_f32 v90, v90, v55, v48
	v_max3_f32 v90, v90, v49, v50
	v_max3_f32 v90, v90, v51, v44
	v_max3_f32 v90, v90, v45, v46
	v_max3_f32 v90, v90, v47, v40
	v_max3_f32 v90, v90, v41, v42
	v_max_f32_e32 v90, v90, v43
	v_mov_b32_e32 v124, v90
	s_nop 1
	v_permlane16_swap_b32_e32 v124, v90
	v_max_f32_e32 v90, v90, v124
	v_mov_b32_e32 v124, v90
	s_nop 1
	v_permlane32_swap_b32_e32 v124, v90
	v_max3_f32 v127, v122, v90, v124
	v_sub_f32_e32 v90, v122, v127
	v_mov_b32_e32 v126, v127
	v_exp_f32_e32 v90, v90
	v_cmp_gt_f32_e32 vcc, v127, v122
	s_cbranch_vccz .Lnsa_fastm_norescale
	v_pk_mul_f32 v[38:39], v[38:39], v[90:91] op_sel_hi:[1,0]
	v_pk_mul_f32 v[36:37], v[36:37], v[90:91] op_sel_hi:[1,0]
	v_pk_mul_f32 v[34:35], v[34:35], v[90:91] op_sel_hi:[1,0]
	v_pk_mul_f32 v[32:33], v[32:33], v[90:91] op_sel_hi:[1,0]
	v_pk_mul_f32 v[30:31], v[30:31], v[90:91] op_sel_hi:[1,0]
	v_pk_mul_f32 v[28:29], v[28:29], v[90:91] op_sel_hi:[1,0]
	v_pk_mul_f32 v[26:27], v[26:27], v[90:91] op_sel_hi:[1,0]
	v_pk_mul_f32 v[24:25], v[24:25], v[90:91] op_sel_hi:[1,0]
.Lnsa_fastm_norescale:
	v_pk_add_f32 v[52:53], v[52:53], v[126:127] neg_lo:[0,1] neg_hi:[0,1]
	v_pk_add_f32 v[54:55], v[54:55], v[126:127] neg_lo:[0,1] neg_hi:[0,1]
	v_pk_add_f32 v[48:49], v[48:49], v[126:127] neg_lo:[0,1] neg_hi:[0,1]
	v_pk_add_f32 v[50:51], v[50:51], v[126:127] neg_lo:[0,1] neg_hi:[0,1]
	v_exp_f32_e32 v128, v52
	v_exp_f32_e32 v129, v53
	v_exp_f32_e32 v130, v54
	v_exp_f32_e32 v131, v55
	v_pk_add_f32 v[44:45], v[44:45], v[126:127] neg_lo:[0,1] neg_hi:[0,1]
	v_pk_add_f32 v[46:47], v[46:47], v[126:127] neg_lo:[0,1] neg_hi:[0,1]
	v_exp_f32_e32 v132, v48
	v_exp_f32_e32 v133, v49
	v_exp_f32_e32 v134, v50
	v_exp_f32_e32 v135, v51
	v_pk_add_f32 v[40:41], v[40:41], v[126:127] neg_lo:[0,1] neg_hi:[0,1]
	v_pk_add_f32 v[42:43], v[42:43], v[126:127] neg_lo:[0,1] neg_hi:[0,1]
	v_exp_f32_e32 v136, v44
	v_exp_f32_e32 v137, v45
	v_exp_f32_e32 v138, v46
	v_exp_f32_e32 v139, v47
	v_exp_f32_e32 v140, v40
	v_exp_f32_e32 v141, v41
	v_exp_f32_e32 v142, v42
	v_exp_f32_e32 v143, v43
	v_cvt_pk_bf16_f32 v248, v128, v129
	v_cvt_pk_bf16_f32 v249, v130, v131
	v_cvt_pk_bf16_f32 v250, v132, v133
	v_cvt_pk_bf16_f32 v251, v134, v135
	v_cvt_pk_bf16_f32 v52, v136, v137
	v_cvt_pk_bf16_f32 v53, v138, v139
	v_cvt_pk_bf16_f32 v54, v140, v141
	v_cvt_pk_bf16_f32 v55, v142, v143
	s_waitcnt lgkmcnt(4)
	v_mfma_f32_16x16x32_bf16 v[36:39], v[212:215], v[248:251], v[36:39]
	v_mfma_f32_16x16x32_bf16 v[32:35], v[216:219], v[248:251], v[32:35]
	v_mfma_f32_16x16x32_bf16 v[28:31], v[220:223], v[248:251], v[28:31]
	v_mfma_f32_16x16x32_bf16 v[24:27], v[224:227], v[248:251], v[24:27]
	v_add_f32_e32 v40, v129, v128
	v_add_f32_e32 v40, v130, v40
	v_add_f32_e32 v40, v131, v40
	v_add_f32_e32 v40, v132, v40
	v_add_f32_e32 v40, v133, v40
	s_waitcnt lgkmcnt(0)
	v_mfma_f32_16x16x32_bf16 v[36:39], v[232:235], v[52:55], v[36:39]
	v_add_f32_e32 v40, v134, v40
	v_add_f32_e32 v40, v135, v40
	v_add_f32_e32 v40, v136, v40
	v_mfma_f32_16x16x32_bf16 v[32:35], v[236:239], v[52:55], v[32:35]
	v_add_f32_e32 v40, v137, v40
	v_add_f32_e32 v40, v138, v40
	v_add_f32_e32 v40, v139, v40
	v_mfma_f32_16x16x32_bf16 v[28:31], v[240:243], v[52:55], v[28:31]
	v_add_f32_e32 v40, v140, v40
	v_add_f32_e32 v40, v141, v40
	v_add_f32_e32 v40, v142, v40
	v_mfma_f32_16x16x32_bf16 v[24:27], v[244:247], v[52:55], v[24:27]
	v_add_f32_e32 v40, v143, v40
	v_fmac_f32_e32 v40, v121, v90
	v_mov_b32_e32 v122, v127
	v_mov_b32_e32 v121, v40
	s_branch .Lnsa_fast_done
.Lnsa_fastm1:
	ds_read_b128 v[176:179], v175 offset:9472
	ds_read_b128 v[180:183], v211 offset:9472
	ds_read_b128 v[184:187], v228 offset:9472
	ds_read_b128 v[188:191], v229 offset:9472
	ds_read_b128 v[192:195], v175 offset:9536
	ds_read_b128 v[196:199], v211 offset:9536
	ds_read_b128 v[200:203], v228 offset:9536
	ds_read_b128 v[204:207], v229 offset:9536
	ds_read_b128 v[212:215], v231 offset:48128
	ds_read_b128 v[216:219], v231 offset:50432
	ds_read_b128 v[220:223], v231 offset:52736
	ds_read_b128 v[224:227], v252 offset:48128
	ds_read_b128 v[232:235], v231 offset:48192
	ds_read_b128 v[236:239], v231 offset:50496
	s_waitcnt lgkmcnt(10)
	v_mfma_f32_16x16x32_bf16 v[52:55], v[176:179], v[4:7], v[152:155]
	v_mfma_f32_16x16x32_bf16 v[48:51], v[180:183], v[4:7], v[156:159]
	ds_read_b128 v[240:243], v231 offset:52800
	v_mfma_f32_16x16x32_bf16 v[44:47], v[184:187], v[4:7], v[160:163]
	ds_read_b128 v[244:247], v252 offset:48192
	v_mfma_f32_16x16x32_bf16 v[40:43], v[188:191], v[4:7], v[164:167]
	s_waitcnt lgkmcnt(8)
	v_mfma_f32_16x16x32_bf16 v[52:55], v[192:195], v[0:3], v[52:55]
	v_mfma_f32_16x16x32_bf16 v[48:51], v[196:199], v[0:3], v[48:51]
	v_mfma_f32_16x16x32_bf16 v[44:47], v[200:203], v[0:3], v[44:47]
	v_mfma_f32_16x16x32_bf16 v[40:43], v[204:207], v[0:3], v[40:43]
	s_nop 4
	v_max3_f32 v90, v52, v53, v54
	v_max3_f32 v90, v90, v55, v48
	v_max3_f32 v90, v90, v49, v50
	v_max3_f32 v90, v90, v51, v44
	v_max3_f32 v90, v90, v45, v46
	v_max3_f32 v90, v90, v47, v40
	v_max3_f32 v90, v90, v41, v42
	v_max_f32_e32 v90, v90, v43
	v_mov_b32_e32 v124, v90
	s_nop 1
	v_permlane16_swap_b32_e32 v124, v90
	v_max_f32_e32 v90, v90, v124
	v_mov_b32_e32 v124, v90
	s_nop 1
	v_permlane32_swap_b32_e32 v124, v90
	v_max3_f32 v127, v122, v90, v124
	v_sub_f32_e32 v90, v122, v127
	v_mov_b32_e32 v126, v127
	v_exp_f32_e32 v90, v90
	v_cmp_gt_f32_e32 vcc, v127, v122
	s_cbranch_vccz .Lnsa_fastm1_norescale
	v_pk_mul_f32 v[38:39], v[38:39], v[90:91] op_sel_hi:[1,0]
	v_pk_mul_f32 v[36:37], v[36:37], v[90:91] op_sel_hi:[1,0]
	v_pk_mul_f32 v[34:35], v[34:35], v[90:91] op_sel_hi:[1,0]
	v_pk_mul_f32 v[32:33], v[32:33], v[90:91] op_sel_hi:[1,0]
	v_pk_mul_f32 v[30:31], v[30:31], v[90:91] op_sel_hi:[1,0]
	v_pk_mul_f32 v[28:29], v[28:29], v[90:91] op_sel_hi:[1,0]
	v_pk_mul_f32 v[26:27], v[26:27], v[90:91] op_sel_hi:[1,0]
	v_pk_mul_f32 v[24:25], v[24:25], v[90:91] op_sel_hi:[1,0]

.Lnsa_fast_norescale:
	v_sub_f32_e32 v52, v52, v127
	v_sub_f32_e32 v53, v53, v127
	v_sub_f32_e32 v54, v54, v127
	v_sub_f32_e32 v55, v55, v127
	v_exp_f32_e32 v128, v52
	v_exp_f32_e32 v129, v53
	v_exp_f32_e32 v130, v54
	v_exp_f32_e32 v131, v55
	v_sub_f32_e32 v48, v48, v127
	v_sub_f32_e32 v49, v49, v127
	v_sub_f32_e32 v50, v50, v127
	v_sub_f32_e32 v51, v51, v127
	v_exp_f32_e32 v132, v48
	v_exp_f32_e32 v133, v49
	v_exp_f32_e32 v134, v50
	v_exp_f32_e32 v135, v51
	v_sub_f32_e32 v44, v44, v127
	v_sub_f32_e32 v45, v45, v127
	v_sub_f32_e32 v46, v46, v127
	v_sub_f32_e32 v47, v47, v127
	v_exp_f32_e32 v136, v44
	v_exp_f32_e32 v137, v45
	v_exp_f32_e32 v138, v46
	v_exp_f32_e32 v139, v47
	v_sub_f32_e32 v40, v40, v127
	v_sub_f32_e32 v41, v41, v127
	v_sub_f32_e32 v42, v42, v127
	v_sub_f32_e32 v43, v43, v127
	v_exp_f32_e32 v140, v40
	v_exp_f32_e32 v141, v41
	v_exp_f32_e32 v142, v42
	v_exp_f32_e32 v143, v43
	v_cvt_pk_bf16_f32 v248, v128, v129
	v_cvt_pk_bf16_f32 v249, v130, v131
	v_cvt_pk_bf16_f32 v250, v132, v133
	v_cvt_pk_bf16_f32 v251, v134, v135
	v_cvt_pk_bf16_f32 v52, v136, v137
	v_cvt_pk_bf16_f32 v53, v138, v139
	v_cvt_pk_bf16_f32 v54, v140, v141
	v_cvt_pk_bf16_f32 v55, v142, v143
	s_waitcnt lgkmcnt(7)
	v_mfma_f32_16x16x32_bf16 v[36:39], v[212:215], v[248:251], v[36:39]
	v_add_f32_e32 v40, v132, v128
	v_add_f32_e32 v41, v133, v129
	s_waitcnt lgkmcnt(6)
	v_mfma_f32_16x16x32_bf16 v[32:35], v[216:219], v[248:251], v[32:35]
	v_add_f32_e32 v42, v134, v130
	v_add_f32_e32 v43, v135, v131
	s_waitcnt lgkmcnt(5)
	v_mfma_f32_16x16x32_bf16 v[28:31], v[220:223], v[248:251], v[28:31]
	v_add_f32_e32 v40, v136, v40
	v_add_f32_e32 v41, v137, v41
	s_waitcnt lgkmcnt(4)
	v_mfma_f32_16x16x32_bf16 v[24:27], v[224:227], v[248:251], v[24:27]
	v_add_f32_e32 v42, v138, v42
	v_add_f32_e32 v43, v139, v43
	s_waitcnt lgkmcnt(3)
	v_mfma_f32_16x16x32_bf16 v[36:39], v[232:235], v[52:55], v[36:39]
	v_add_f32_e32 v40, v140, v40
	v_add_f32_e32 v41, v141, v41
	s_waitcnt lgkmcnt(2)
	v_mfma_f32_16x16x32_bf16 v[32:35], v[236:239], v[52:55], v[32:35]
	v_add_f32_e32 v42, v142, v42
	v_add_f32_e32 v43, v143, v43
	s_waitcnt lgkmcnt(1)
	v_mfma_f32_16x16x32_bf16 v[28:31], v[240:243], v[52:55], v[28:31]
	v_add_f32_e32 v40, v40, v41
	v_fmac_f32_e32 v40, v121, v90
	s_waitcnt lgkmcnt(0)
	v_mfma_f32_16x16x32_bf16 v[24:27], v[244:247], v[52:55], v[24:27]
	v_add_f32_e32 v42, v42, v43
	v_mov_b32_e32 v122, v127
	v_add_f32_e32 v121, v42, v40
	s_branch .Lnsa_fast_done
.Lnsa_fast_done:
	s_andn2_b64 vcc, exec, s[52:53]
	s_xor_b32 s63, s63, 1
	s_cbranch_vccz .LBB0_594
	s_branch .LBB0_595
